# both FFN1-down conversions out of P0: layer 0 in step-0 tail (instead of FFN2-down l0, which moves to step-7 tail), layer 1 in step-2 tail; in-proj rotation retuned
# speedup vs baseline: 1.0179x; 1.0028x over previous
; #define PG8_LAS __attribute__((address_space(3)))
; #define LAS __attribute__((address_space(3)))
; __device__ __forceinline__ LAS unsigned char* lds_base() { extern __shared__ __attribute__((aligned(16))) unsigned char lds_any_[]; return (LAS unsigned char*)lds_any_; }
; __global__ void __launch_bounds__(512, 2) fwd_megakernel(Args args) {
;     extern __shared__ __attribute__((aligned(16))) unsigned char lds[];
;     cg::grid_group grid = cg::this_grid();
;     const int G = gridDim.x, bx = blockIdx.x;
;     PG8_LAS unsigned char* ring = (PG8_LAS unsigned char*)lds;
;     { volatile LAS unsigned* bst = (volatile LAS unsigned*)(lds_base() + (LDS_BYTES - 64));
;       if (threadIdx.x < 2) bst[threadIdx.x] = 0u;
;       if (bx == 0) { unsigned* barw = (unsigned*)(args.ws + WS_BAR); for (int i = threadIdx.x; i < BARW_TOTAL; i += 512) barw[i] = 0u; } }
_Z14fwd_megakernel4Args:
	s_load_dwordx2 s[72:73], s[0:1], 0xe8
	s_add_u32 s28, s0, 0xe8
	v_and_b32_e32 v202, 0x3ff, v0
	s_mov_b32 s58, s2
	s_addc_u32 s29, s1, 0
	v_cmp_gt_u32_e32 vcc, 2, v202
	s_and_saveexec_b64 s[4:5], vcc
	v_lshl_add_u32 v1, v202, 2, 0
	v_add_u32_e32 v1, 0x23fc0, v1
	v_mov_b32_e32 v2, 0
	ds_write_b32 v1, v2
	s_or_b64 exec, exec, s[4:5]
	s_mov_b32 s4, 1
	v_writelane_b32 v255, s4, 62
	s_load_dwordx2 s[56:57], s[0:1], 0xe0
	s_cmp_lg_u32 s58, 0
	s_mov_b32 s45, 0
	s_cbranch_scc1 .LBB0_9
	v_lshrrev_b32_e32 v1, 9, v202
	v_sub_u32_e32 v6, 16, v1
	s_waitcnt lgkmcnt(0)
	s_add_u32 s4, s56, 0x277b6800
	v_and_b32_e32 v1, 30, v6
	v_add_u32_e32 v203, 0x200, v202
	s_addc_u32 s5, s57, 0
	s_mov_b64 s[6:7], 0
	v_mov_b32_e32 v3, 0
	v_mov_b32_e32 v7, v1
	v_mov_b64_e32 v[4:5], v[202:203]

; __device__ __forceinline__ void conv_set(const CvPtrs args, unsigned char* ws, int l, unsigned mask, LAS float* scr, int gw, int NGW, int lane) {
;     ...
;     if (mask & CV_D1) p0_matrix(0, args.in[5] + (size_t)l * FF * D, nullptr, FF, D, D, (bf16*)(lw + LW_D1), scr, gw, NGW, lane, nullptr);
.LBB0_47:
	s_branch .LBB0_50
	s_andn2_b64 vcc, exec, s[46:47]
	s_cbranch_vccnz .LBB0_50
	s_mul_i32 s2, s44, 0x2b00000
	s_add_u32 s80, s20, s2
	s_addc_u32 s81, s21, 0
	s_add_u32 s82, s77, 0x2b00000
	s_addc_u32 s83, s90, 0
	s_mov_b32 s86, s59
	s_mov_b32 s87, s30
	s_cmpk_lg_i32 s34, 0x800
	s_cbranch_scc1 .Lrot_d1_skip
	s_mul_i32 s2, s44, 0x3c0
	s_add_i32 s87, s30, s2
	s_addk_i32 s87, 0x80
	s_and_b32 s87, s87, 0x7ff
	s_lshl_b32 s86, s87, 6

; #define LAS __attribute__((address_space(3)))
; __device__ __forceinline__ void p0_matrix(int type  , const float* W0, const float* W1, int K, int Nsrc, int Ndst, bf16* dst, LAS float* scr, int gw, int NGW, int lane, const float* gain) {
;     const int nruns = Ndst >> 6, nitems = (K >> 6) * nruns;
;     for (int it = gw; it < nitems; it += NGW) {
;         const int kb = it / nruns, nb = it - kb * nruns, n0 = nb * 64, k0 = kb * 64;
; __device__ __forceinline__ void conv_set(const CvPtrs args, unsigned char* ws, int l, unsigned mask, LAS float* scr, int gw, int NGW, int lane) {
;     ...
;     if (mask & CV_WIN) p0_matrix(2, args.in[7] + (size_t)l * D * INW, nullptr, D, INW, INP, (bf16*)(lw + LW_IN), scr, gw, NGW, lane, args.in[6] + (size_t)l * D);
.LBB0_50:
	s_andn2_b64 vcc, exec, s[74:75]
	s_cbranch_vccnz .LBB0_150
	s_andn2_b64 vcc, exec, s[52:53]
	s_cbranch_vccnz .LBB0_150
	s_mul_i32 s2, s44, 0x4460000
	s_add_u32 s91, s24, s2
	s_addc_u32 s92, s25, 0
	s_add_u32 s77, s77, 0x4080000
	s_addc_u32 s90, s90, 0
	s_mov_b32 s93, s59
	s_mov_b32 s94, s30
	s_cmpk_lg_i32 s34, 0x800
	s_cbranch_scc1 .Lrot_win_skip
	s_add_i32 s94, s30, 0x180
	s_and_b32 s94, s94, 0x7ff
	s_lshl_b32 s93, s94, 6

; #define LAS __attribute__((address_space(3)))
; __device__ __forceinline__ LAS unsigned char* lds_base() { extern __shared__ __attribute__((aligned(16))) unsigned char lds_any_[]; return (LAS unsigned char*)lds_any_; }
; #define OPQ_V(x) asm volatile("" : "+v"(x))
; #define OPQ_P(x) do { unsigned long long t_ = (unsigned long long)(x); asm volatile("" : "+s"(t_)); x = (decltype(x))(GASP unsigned char*)t_; } while (0)
; __global__ void __launch_bounds__(512, 2) fwd_megakernel(Args args) {
;     ...
;         {
;             unsigned tmask = 0u; int tl = l;
;             if (k == 0) tmask = l == 0 ? (CV_SMALL | CV_D2) : (CV_SMALL | CV_WIN);
;             else if (k == 2) tmask = CV_GU2;
;             else if (k == 7) { if (l == 0) { tl = 1; tmask = CV_GU1; } else tmask = CV_D2; }
;             if (tmask) {
;                 const int nleft = ((M / 256) * ((k == 2 ? INP : 2 * FF) / 256)) % G;
;                 if (bx >= nleft) {
;                     __syncthreads();
;                     int tid_ = threadIdx.x; OPQ_V(tid_); const int lane = tid_ & 63, wave = __builtin_amdgcn_readfirstlane(tid_ >> 6);
;                     LAS float* scr = (LAS float*)(lds_base() + wave * 16640);
;                     unsigned char* ws2 = args.ws; OPQ_P(ws2);
;                     conv_set(CV_ARGS(args), ws2, tl, tmask, scr, (bx - nleft) * 8 + wave, (G - nleft) * 8, lane);
;                 }
;             }
.LBB0_1624:
	v_readlane_b32 s0, v255, 62
	s_nop 3
	s_cmp_lg_u32 s89, 0
	s_cbranch_scc1 .Ltl_s2
	s_cmp_lg_u32 s0, 1
	s_cbranch_scc1 .Ltl_done
	s_mov_b32 s0, 0
	v_writelane_b32 v255, s0, 62
	s_branch .Ltl_done
.Ltl_s2:
	s_cmp_lg_u32 s89, 2
	s_cbranch_scc1 .Ltl_s7
	s_cmp_lg_u32 s0, 0
	s_cbranch_scc1 .Ltl_s2b
	s_mov_b32 s0, 1
	v_writelane_b32 v255, s0, 62
	v_readlane_b32 s62, v253, 1
	v_readlane_b32 s63, v253, 2
	v_readlane_b32 s34, v255, 19
	v_readlane_b32 s35, v255, 20
	s_mov_b32 s3, 2
	s_mov_b32 s19, 0x80
	s_mov_b32 s20, 1
	s_branch .LBB0_1413
.Ltl_s2b:
	s_cmp_lg_u32 s0, 1
	s_cbranch_scc1 .Ltl_done
	s_mov_b32 s0, 2
	v_writelane_b32 v255, s0, 62
	s_branch .Ltl_done
.Ltl_s7:
	s_cmp_lg_u32 s89, 7
	s_cbranch_scc1 .Ltl_done
	s_cmp_lg_u32 s0, 2
	s_cbranch_scc1 .Ltl_s7b
	s_mov_b32 s0, 3
	v_writelane_b32 v255, s0, 62
	v_readlane_b32 s62, v253, 1
	v_readlane_b32 s63, v253, 2
	v_readlane_b32 s34, v255, 19
	v_readlane_b32 s35, v255, 20
	s_mov_b32 s3, 7
	s_mov_b32 s19, 0x80
	s_mov_b32 s20, 0
	s_branch .LBB0_1413
.Ltl_s7b:
	s_cmp_lg_u32 s0, 3
	s_cbranch_scc1 .Ltl_done
	s_mov_b32 s0, 4
	v_writelane_b32 v255, s0, 62
